# P0 weight conversion loop: next tile's global loads issued before this tile's convert+LDS-write phase (data copied to a second register set)
# speedup vs baseline: 1.0048x; 1.0048x over previous
; #define LAS __attribute__((address_space(3)))
; #define P0_LOAD() do { _Pragma("unroll") for (int i_ = 0; i_ < 4; ++i_) { const int kk_ = (tid >> 4) + 32 * i_; \
;         v[i_] = __builtin_nontemporal_load((const f32x4*)(src + (size_t)(k0 + kk_) * N + n0 + (tid & 15) * 4)); sc[i_] = scale ? scale[k0 + kk_] : 1.0f; } } while (0)
; __device__ void phase0(const Params& p, LAS unsigned char* lds, const int WID) {
;     ...
;     const float* src = nullptr; bf16_t* dst = nullptr; const float* scale = nullptr; int K = 0, N = 0, mode = 0, k0 = 0, n0 = 0;
;     ...
;     f32x4 v[4]; float sc[4];
;     int job = bx, buf = 0;
;     if (job < J5) { P0_DECODE(job); P0_LOAD(); }
;     __syncthreads();
;     while (job < J5) {
;         LAS bf16_t* tl = (LAS bf16_t*)(lds + buf * 17408);
;         const int nn = (tid & 15) * 4;
.LBB0_30:
	s_add_u32 s0, s94, 0x6e00000
	s_addc_u32 s1, s95, 0
	v_writelane_b32 v254, s0, 13
	s_barrier
	s_nop 0
	v_writelane_b32 v254, s1, 14
	s_add_u32 s0, s94, 0x6600000
	s_addc_u32 s1, s95, 0
	v_writelane_b32 v254, s0, 15
	s_andn2_b64 vcc, exec, s[12:13]
	s_nop 0
	v_writelane_b32 v254, s1, 16
	s_cbranch_vccnz .LBB0_63
	v_lshlrev_b32_e32 v19, 4, v42
	v_and_b32_e32 v18, 60, v26
	v_ashrrev_i32_e32 v30, 4, v20
	s_movk_i32 s0, 0x110
	v_ashrrev_i32_e32 v32, 3, v20
	v_and_b32_e32 v20, 0x70, v19
	v_mul_u32_u24_e32 v31, 0x110, v18
	v_mov_b32_e32 v27, 0
	v_mul_lo_u32 v33, v32, s0
	v_lshlrev_b32_e32 v34, 1, v20
	s_mov_b32 s11, 0
	v_lshlrev_b32_e32 v35, 1, v30
	v_lshlrev_b32_e32 v26, 2, v18
	s_movk_i32 s23, 0x1600
	v_lshlrev_b32_e32 v28, 1, v20
	v_mov_b32_e32 v36, 0x80
	s_mov_b32 s24, s2
	s_mov_b64 s[14:15], s[6:7]
	s_mov_b32 s25, s9
	s_mov_b32 s27, s22
	s_waitcnt vmcnt(0)
	s_branch .LBB0_33

; #define LAS __attribute__((address_space(3)))
; __device__ __forceinline__ unsigned cvt_pk_bf16(float lo, float hi) { unsigned r; asm volatile("v_cvt_pk_bf16_f32 %0, %1, %2" : "=v"(r) : "v"(lo), "v"(hi)); return r; }
; #define P0_LOAD() do { _Pragma("unroll") for (int i_ = 0; i_ < 4; ++i_) { const int kk_ = (tid >> 4) + 32 * i_; \
;         v[i_] = __builtin_nontemporal_load((const f32x4*)(src + (size_t)(k0 + kk_) * N + n0 + (tid & 15) * 4)); sc[i_] = scale ? scale[k0 + kk_] : 1.0f; } } while (0)
; __device__ void phase0(const Params& p, LAS unsigned char* lds, const int WID) {
;     ...
;     while (job < J5) {
;         LAS bf16_t* tl = (LAS bf16_t*)(lds + buf * 17408);
;         const int nn = (tid & 15) * 4;
; #pragma unroll
;         for (int i = 0; i < 4; ++i) { const int kk = (tid >> 4) + 32 * i; const unsigned w0 = cvt_pk_bf16(v[i][0] * sc[i], v[i][1] * sc[i]), w1 = cvt_pk_bf16(v[i][2] * sc[i], v[i][3] * sc[i]);
;             tl[(nn + 0) * 136 + kk] = (bf16_t)(w0 & 0xffff); tl[(nn + 1) * 136 + kk] = (bf16_t)(w0 >> 16); tl[(nn + 2) * 136 + kk] = (bf16_t)(w1 & 0xffff); tl[(nn + 3) * 136 + kk] = (bf16_t)(w1 >> 16); }
;         bf16_t* cdst = dst; const int cK = K, cmode = mode, ck0 = k0, cn0 = n0;
;         const int nxt = job + G;
;         if (nxt < J5) { P0_DECODE(nxt); P0_LOAD(); }
.LBB0_33:
	s_mul_i32 s0, s11, 0x4400
	s_add_i32 s26, s0, 0
	s_add_i32 s24, s24, s96
	s_cmpk_gt_i32 s24, 0x1bbf
	s_cselect_b64 s[12:13], -1, 0
	s_mov_b32 s28, s8
	s_mov_b32 s20, s10
	s_waitcnt vmcnt(2)
	v_mov_b64_e32 v[46:47], v[2:3]
	v_mov_b64_e32 v[48:49], v[4:5]
	v_mov_b64_e32 v[50:51], v[6:7]
	v_mov_b64_e32 v[52:53], v[8:9]
	v_mov_b64_e32 v[54:55], v[10:11]
	v_mov_b64_e32 v[56:57], v[12:13]
	v_mov_b64_e32 v[58:59], v[14:15]
	v_mov_b64_e32 v[60:61], v[16:17]
	v_mov_b32_e32 v62, v38
	v_mov_b32_e32 v63, v37
	v_mov_b32_e32 v64, v40
	v_mov_b32_e32 v65, v39
	s_and_b64 vcc, exec, s[12:13]
	s_cbranch_vccnz .Lp0_proc
	s_cmpk_lt_i32 s24, 0x700
	s_cbranch_scc1 .LBB0_40
	s_cmpk_gt_u32 s24, 0x8ff
	s_cbranch_scc0 .LBB0_41
	s_cmpk_gt_u32 s24, 0x13ff
	s_cbranch_scc0 .LBB0_42
	s_cmpk_gt_u32 s24, 0x197f
	s_cbranch_scc0 .LBB0_44
	s_cmpk_gt_u32 s24, 0x1b7f
	s_cbranch_scc0 .LBB0_45
	s_add_i32 s28, s24, 0xffffe480
	s_mov_b64 s[14:15], 0
	s_mov_b64 s[0:1], 0
	s_mov_b64 s[16:17], s[86:87]
	s_branch .LBB0_46

; __device__ __forceinline__ unsigned cvt_pk_bf16(float lo, float hi) { unsigned r; asm volatile("v_cvt_pk_bf16_f32 %0, %1, %2" : "=v"(r) : "v"(lo), "v"(hi)); return r; }
; __device__ void phase0(const Params& p, LAS unsigned char* lds, const int WID) {
;     ...
; #pragma unroll
;         for (int i = 0; i < 4; ++i) { const int kk = (tid >> 4) + 32 * i; const unsigned w0 = cvt_pk_bf16(v[i][0] * sc[i], v[i][1] * sc[i]), w1 = cvt_pk_bf16(v[i][2] * sc[i], v[i][3] * sc[i]);
;             tl[(nn + 0) * 136 + kk] = (bf16_t)(w0 & 0xffff); tl[(nn + 1) * 136 + kk] = (bf16_t)(w0 >> 16); tl[(nn + 2) * 136 + kk] = (bf16_t)(w1 & 0xffff); tl[(nn + 3) * 136 + kk] = (bf16_t)(w1 >> 16); }
.Lp0_proc:
	v_mul_f32_e32 v18, v46, v62
	v_mul_f32_e32 v19, v47, v62
	v_cvt_pk_bf16_f32 v18, v18, v19
	v_mul_f32_e32 v19, v48, v62
	v_mul_f32_e32 v20, v49, v62
	v_cvt_pk_bf16_f32 v19, v19, v20
	v_add3_u32 v20, s26, v31, v35
	ds_write_b16 v20, v18
	ds_write_b16_d16_hi v20, v18 offset:272
	ds_write_b16 v20, v19 offset:544
	ds_write_b16_d16_hi v20, v19 offset:816
	v_mul_f32_e32 v18, v50, v63
	v_mul_f32_e32 v19, v51, v63
	v_cvt_pk_bf16_f32 v18, v18, v19
	v_mul_f32_e32 v19, v52, v63
	v_mul_f32_e32 v21, v53, v63
	v_cvt_pk_bf16_f32 v19, v19, v21
	ds_write_b16 v20, v18 offset:64
	ds_write_b16_d16_hi v20, v18 offset:336
	ds_write_b16 v20, v19 offset:608
	ds_write_b16_d16_hi v20, v19 offset:880
	v_mul_f32_e32 v18, v54, v64
	v_mul_f32_e32 v19, v55, v64
	v_cvt_pk_bf16_f32 v18, v18, v19
	v_mul_f32_e32 v19, v56, v64
	v_mul_f32_e32 v21, v57, v64
	v_cvt_pk_bf16_f32 v19, v19, v21
	ds_write_b16 v20, v18 offset:128
	ds_write_b16_d16_hi v20, v18 offset:400
	ds_write_b16 v20, v19 offset:672
	ds_write_b16_d16_hi v20, v19 offset:944
	v_mul_f32_e32 v18, v58, v65
	v_mul_f32_e32 v19, v59, v65
	v_cvt_pk_bf16_f32 v18, v18, v19
	v_mul_f32_e32 v19, v60, v65
	v_mul_f32_e32 v21, v61, v65
	v_cvt_pk_bf16_f32 v19, v19, v21
	ds_write_b16 v20, v18 offset:192
	ds_write_b16_d16_hi v20, v18 offset:464
	ds_write_b16 v20, v19 offset:736
	ds_write_b16_d16_hi v20, v19 offset:1008
